# gate/up K-loop: relaxed first-iteration waits moved out of line so the common path takes no branch
# baseline (speedup 1.0000x reference)
.LBB0_893:
	s_add_u32 s20, s4, 0xfffc0080
	s_addc_u32 s21, s5, -1
	s_add_i32 s41, 0, 0x10000
	s_cmp_eq_u32 s40, 12
	s_cselect_b32 s23, s15, s21
	s_cselect_b32 s22, s36, s20
	s_cselect_b32 s21, s11, s39
	s_cselect_b32 s20, s37, s38
	s_add_i32 s44, 0, 0x14000
	v_add_u32_e32 v156, s41, v171
	v_add_u32_e32 v164, s44, v171
	ds_read_b128 v[134:137], v156
	ds_read_b128 v[148:151], v156 offset:1024
	ds_read_b128 v[152:155], v156 offset:2048
	ds_read_b128 v[156:159], v156 offset:3072
	ds_read_b128 v[160:163], v164
	ds_read_b128 v[182:185], v164 offset:1024
	ds_read_b128 v[186:189], v164 offset:2048
	ds_read_b128 v[190:193], v164 offset:3072
	v_lshl_add_u64 v[226:227], s[4:5], 0, v[144:145]
	s_add_i32 m0, s26, 0xc000
	ds_read_b128 v[194:197], v175
	ds_read_b128 v[198:201], v175 offset:1024
	ds_read_b128 v[202:205], v175 offset:2048
	ds_read_b128 v[206:209], v175 offset:3072
	ds_read_b128 v[210:213], v175 offset:4096
	ds_read_b128 v[214:217], v175 offset:5120
	ds_read_b128 v[218:221], v175 offset:6144
	ds_read_b128 v[222:225], v175 offset:7168
	global_load_lds_dwordx4 v[226:227], off
	v_lshl_add_u64 v[226:227], s[4:5], 0, v[146:147]
	s_add_i32 m0, s26, 0xe000
	s_nop 0
	global_load_lds_dwordx4 v[226:227], off
	s_cmp_eq_i32 s40, -2
	s_cselect_b32 s98, s2, 0
	s_cmp_lg_u32 s98, 0
	s_cbranch_scc1 .Lg3_relax_w1
	s_waitcnt vmcnt(8)
.Lg3_join_w1:
	s_waitcnt lgkmcnt(0)
	s_barrier
	s_setprio 1
	s_waitcnt lgkmcnt(0)
	v_mfma_f32_16x16x32_bf16 v[130:133], v[134:137], v[194:197], v[130:133]
	v_mfma_f32_16x16x32_bf16 v[130:133], v[148:151], v[198:201], v[130:133]
	v_mfma_f32_16x16x32_bf16 v[122:125], v[152:155], v[194:197], v[122:125]
	v_mfma_f32_16x16x32_bf16 v[122:125], v[156:159], v[198:201], v[122:125]
	v_mfma_f32_16x16x32_bf16 v[114:117], v[134:137], v[202:205], v[114:117]
	v_mfma_f32_16x16x32_bf16 v[114:117], v[148:151], v[206:209], v[114:117]
	v_mfma_f32_16x16x32_bf16 v[106:109], v[152:155], v[202:205], v[106:109]
	v_mfma_f32_16x16x32_bf16 v[106:109], v[156:159], v[206:209], v[106:109]
	v_mfma_f32_16x16x32_bf16 v[98:101], v[134:137], v[210:213], v[98:101]
	v_mfma_f32_16x16x32_bf16 v[98:101], v[148:151], v[214:217], v[98:101]
	v_mfma_f32_16x16x32_bf16 v[90:93], v[152:155], v[210:213], v[90:93]
	v_mfma_f32_16x16x32_bf16 v[90:93], v[156:159], v[214:217], v[90:93]
	v_mfma_f32_16x16x32_bf16 v[82:85], v[134:137], v[218:221], v[82:85]
	v_mfma_f32_16x16x32_bf16 v[82:85], v[148:151], v[222:225], v[82:85]
	v_mfma_f32_16x16x32_bf16 v[74:77], v[152:155], v[218:221], v[74:77]
	v_mfma_f32_16x16x32_bf16 v[74:77], v[156:159], v[222:225], v[74:77]
	s_setprio 0
	s_setprio 1
	v_mfma_f32_16x16x32_bf16 v[126:129], v[160:163], v[194:197], v[126:129]
	v_mfma_f32_16x16x32_bf16 v[126:129], v[182:185], v[198:201], v[126:129]
	v_mfma_f32_16x16x32_bf16 v[118:121], v[186:189], v[194:197], v[118:121]
	v_mfma_f32_16x16x32_bf16 v[118:121], v[190:193], v[198:201], v[118:121]
	v_mfma_f32_16x16x32_bf16 v[110:113], v[160:163], v[202:205], v[110:113]
	v_mfma_f32_16x16x32_bf16 v[110:113], v[182:185], v[206:209], v[110:113]
	v_mfma_f32_16x16x32_bf16 v[102:105], v[186:189], v[202:205], v[102:105]
	v_mfma_f32_16x16x32_bf16 v[102:105], v[190:193], v[206:209], v[102:105]
	v_mfma_f32_16x16x32_bf16 v[94:97], v[160:163], v[210:213], v[94:97]
	v_mfma_f32_16x16x32_bf16 v[94:97], v[182:185], v[214:217], v[94:97]
	v_mfma_f32_16x16x32_bf16 v[86:89], v[186:189], v[210:213], v[86:89]
	v_mfma_f32_16x16x32_bf16 v[86:89], v[190:193], v[214:217], v[86:89]
	v_mfma_f32_16x16x32_bf16 v[78:81], v[160:163], v[218:221], v[78:81]
	v_mfma_f32_16x16x32_bf16 v[78:81], v[182:185], v[222:225], v[78:81]
	v_mfma_f32_16x16x32_bf16 v[70:73], v[186:189], v[218:221], v[70:73]
	v_mfma_f32_16x16x32_bf16 v[70:73], v[190:193], v[222:225], v[70:73]
	s_setprio 0
	s_barrier
	s_add_i32 s41, s41, s13
	v_lshl_add_u64 v[226:227], s[20:21], 0, v[0:1]
	s_mov_b32 m0, s41
	ds_read_b128 v[194:197], v175 offset:16384
	ds_read_b128 v[198:201], v175 offset:17408
	ds_read_b128 v[202:205], v175 offset:18432
	ds_read_b128 v[206:209], v175 offset:19456
	ds_read_b128 v[210:213], v175 offset:20480
	ds_read_b128 v[214:217], v175 offset:21504
	ds_read_b128 v[218:221], v175 offset:22528
	ds_read_b128 v[222:225], v175 offset:23552
	global_load_lds_dwordx4 v[226:227], off
	s_add_i32 m0, s41, 0x2000
	s_add_u32 s42, s20, 0x40000
	v_lshl_add_u64 v[228:229], s[20:21], 0, v[14:15]
	s_addc_u32 s43, s21, 0
	s_add_i32 s41, s44, s13
	global_load_lds_dwordx4 v[228:229], off
	v_lshl_add_u64 v[230:231], s[42:43], 0, v[0:1]
	s_mov_b32 m0, s41
	v_lshl_add_u64 v[232:233], s[22:23], 0, v[138:139]
	global_load_lds_dwordx4 v[230:231], off
	v_lshl_add_u64 v[230:231], s[42:43], 0, v[14:15]
	s_add_i32 m0, s41, 0x2000
	s_nop 0
	global_load_lds_dwordx4 v[230:231], off
	v_lshl_add_u64 v[230:231], s[22:23], 0, v[140:141]
	s_mov_b32 m0, s26
	s_nop 0
	global_load_lds_dwordx4 v[230:231], off
	s_mov_b32 m0, s27
	s_nop 0
	global_load_lds_dwordx4 v[232:233], off
	s_cmp_eq_i32 s40, -2
	s_cselect_b32 s98, s2, 0
	s_cmp_lg_u32 s98, 0
	s_cbranch_scc1 .Lg3_relax_w2
	s_waitcnt vmcnt(8)
.Lg3_join_w2:
	s_waitcnt lgkmcnt(0)
	s_barrier
	s_setprio 1
	s_waitcnt lgkmcnt(0)
	v_mfma_f32_16x16x32_bf16 v[66:69], v[134:137], v[194:197], v[66:69]
	v_mfma_f32_16x16x32_bf16 v[66:69], v[148:151], v[198:201], v[66:69]
	v_mfma_f32_16x16x32_bf16 v[58:61], v[152:155], v[194:197], v[58:61]
	v_mfma_f32_16x16x32_bf16 v[58:61], v[156:159], v[198:201], v[58:61]
	v_mfma_f32_16x16x32_bf16 v[50:53], v[134:137], v[202:205], v[50:53]
	v_mfma_f32_16x16x32_bf16 v[50:53], v[148:151], v[206:209], v[50:53]
	v_mfma_f32_16x16x32_bf16 v[42:45], v[152:155], v[202:205], v[42:45]
	v_mfma_f32_16x16x32_bf16 v[42:45], v[156:159], v[206:209], v[42:45]
	v_mfma_f32_16x16x32_bf16 v[34:37], v[134:137], v[210:213], v[34:37]
	v_mfma_f32_16x16x32_bf16 v[34:37], v[148:151], v[214:217], v[34:37]
	v_mfma_f32_16x16x32_bf16 v[26:29], v[152:155], v[210:213], v[26:29]
	v_mfma_f32_16x16x32_bf16 v[26:29], v[156:159], v[214:217], v[26:29]
	v_mfma_f32_16x16x32_bf16 v[18:21], v[134:137], v[218:221], v[18:21]
	v_mfma_f32_16x16x32_bf16 v[18:21], v[148:151], v[222:225], v[18:21]
	v_mfma_f32_16x16x32_bf16 v[6:9], v[152:155], v[218:221], v[6:9]
	v_mfma_f32_16x16x32_bf16 v[6:9], v[156:159], v[222:225], v[6:9]
	s_setprio 0
	s_setprio 1
	v_mfma_f32_16x16x32_bf16 v[62:65], v[160:163], v[194:197], v[62:65]
	v_mfma_f32_16x16x32_bf16 v[62:65], v[182:185], v[198:201], v[62:65]
	v_mfma_f32_16x16x32_bf16 v[54:57], v[186:189], v[194:197], v[54:57]
	v_mfma_f32_16x16x32_bf16 v[54:57], v[190:193], v[198:201], v[54:57]
	v_mfma_f32_16x16x32_bf16 v[46:49], v[160:163], v[202:205], v[46:49]
	v_mfma_f32_16x16x32_bf16 v[46:49], v[182:185], v[206:209], v[46:49]
	v_mfma_f32_16x16x32_bf16 v[38:41], v[186:189], v[202:205], v[38:41]
	v_mfma_f32_16x16x32_bf16 v[38:41], v[190:193], v[206:209], v[38:41]
	v_mfma_f32_16x16x32_bf16 v[30:33], v[160:163], v[210:213], v[30:33]
	v_mfma_f32_16x16x32_bf16 v[30:33], v[182:185], v[214:217], v[30:33]
	v_mfma_f32_16x16x32_bf16 v[22:25], v[186:189], v[210:213], v[22:25]
	v_mfma_f32_16x16x32_bf16 v[22:25], v[190:193], v[214:217], v[22:25]
	v_mfma_f32_16x16x32_bf16 v[10:13], v[160:163], v[218:221], v[10:13]
	v_mfma_f32_16x16x32_bf16 v[10:13], v[182:185], v[222:225], v[10:13]
	v_mfma_f32_16x16x32_bf16 v[2:5], v[186:189], v[218:221], v[2:5]
	v_mfma_f32_16x16x32_bf16 v[2:5], v[190:193], v[222:225], v[2:5]
	s_setprio 0
	s_barrier
	s_add_i32 s41, 0, 0x18000
	s_add_i32 s42, 0, 0x1c000
	v_add_u32_e32 v156, s41, v171
	v_add_u32_e32 v164, s42, v171
	ds_read_b128 v[134:137], v156
	ds_read_b128 v[148:151], v156 offset:1024
	ds_read_b128 v[152:155], v156 offset:2048
	ds_read_b128 v[156:159], v156 offset:3072
	ds_read_b128 v[160:163], v164
	ds_read_b128 v[182:185], v164 offset:1024
	ds_read_b128 v[186:189], v164 offset:2048
	ds_read_b128 v[190:193], v164 offset:3072
	s_add_u32 s22, s22, 0x40000
	s_addc_u32 s23, s23, 0
	s_mov_b32 m0, s28
	v_lshl_add_u64 v[234:235], s[22:23], 0, v[140:141]
	ds_read_b128 v[194:197], v175 offset:32768
	ds_read_b128 v[198:201], v175 offset:33792
	ds_read_b128 v[202:205], v175 offset:34816
	ds_read_b128 v[206:209], v175 offset:35840
	ds_read_b128 v[210:213], v175 offset:36864
	ds_read_b128 v[214:217], v175 offset:37888
	ds_read_b128 v[218:221], v175 offset:38912
	ds_read_b128 v[222:225], v175 offset:39936
	global_load_lds_dwordx4 v[234:235], off
	v_lshl_add_u64 v[234:235], s[22:23], 0, v[138:139]
	s_mov_b32 m0, s29
	s_nop 0
	global_load_lds_dwordx4 v[234:235], off
	s_waitcnt vmcnt(8)
	s_waitcnt lgkmcnt(0)
	s_barrier
	s_setprio 1
	s_waitcnt lgkmcnt(0)
	v_mfma_f32_16x16x32_bf16 v[130:133], v[134:137], v[194:197], v[130:133]
	v_mfma_f32_16x16x32_bf16 v[130:133], v[148:151], v[198:201], v[130:133]
	v_mfma_f32_16x16x32_bf16 v[122:125], v[152:155], v[194:197], v[122:125]
	v_mfma_f32_16x16x32_bf16 v[122:125], v[156:159], v[198:201], v[122:125]
	v_mfma_f32_16x16x32_bf16 v[114:117], v[134:137], v[202:205], v[114:117]
	v_mfma_f32_16x16x32_bf16 v[114:117], v[148:151], v[206:209], v[114:117]
	v_mfma_f32_16x16x32_bf16 v[106:109], v[152:155], v[202:205], v[106:109]
	v_mfma_f32_16x16x32_bf16 v[106:109], v[156:159], v[206:209], v[106:109]
	v_mfma_f32_16x16x32_bf16 v[98:101], v[134:137], v[210:213], v[98:101]
	v_mfma_f32_16x16x32_bf16 v[98:101], v[148:151], v[214:217], v[98:101]
	v_mfma_f32_16x16x32_bf16 v[90:93], v[152:155], v[210:213], v[90:93]
	v_mfma_f32_16x16x32_bf16 v[90:93], v[156:159], v[214:217], v[90:93]
	v_mfma_f32_16x16x32_bf16 v[82:85], v[134:137], v[218:221], v[82:85]
	v_mfma_f32_16x16x32_bf16 v[82:85], v[148:151], v[222:225], v[82:85]
	v_mfma_f32_16x16x32_bf16 v[74:77], v[152:155], v[218:221], v[74:77]
	v_mfma_f32_16x16x32_bf16 v[74:77], v[156:159], v[222:225], v[74:77]
	s_setprio 0
	s_setprio 1
	v_mfma_f32_16x16x32_bf16 v[126:129], v[160:163], v[194:197], v[126:129]
	v_mfma_f32_16x16x32_bf16 v[126:129], v[182:185], v[198:201], v[126:129]
	v_mfma_f32_16x16x32_bf16 v[118:121], v[186:189], v[194:197], v[118:121]
	v_mfma_f32_16x16x32_bf16 v[118:121], v[190:193], v[198:201], v[118:121]
	v_mfma_f32_16x16x32_bf16 v[110:113], v[160:163], v[202:205], v[110:113]
	v_mfma_f32_16x16x32_bf16 v[110:113], v[182:185], v[206:209], v[110:113]
	v_mfma_f32_16x16x32_bf16 v[102:105], v[186:189], v[202:205], v[102:105]
	v_mfma_f32_16x16x32_bf16 v[102:105], v[190:193], v[206:209], v[102:105]
	v_mfma_f32_16x16x32_bf16 v[94:97], v[160:163], v[210:213], v[94:97]
	v_mfma_f32_16x16x32_bf16 v[94:97], v[182:185], v[214:217], v[94:97]
	v_mfma_f32_16x16x32_bf16 v[86:89], v[186:189], v[210:213], v[86:89]
	v_mfma_f32_16x16x32_bf16 v[86:89], v[190:193], v[214:217], v[86:89]
	v_mfma_f32_16x16x32_bf16 v[78:81], v[160:163], v[218:221], v[78:81]
	v_mfma_f32_16x16x32_bf16 v[78:81], v[182:185], v[222:225], v[78:81]
	v_mfma_f32_16x16x32_bf16 v[70:73], v[186:189], v[218:221], v[70:73]
	v_mfma_f32_16x16x32_bf16 v[70:73], v[190:193], v[222:225], v[70:73]
	s_setprio 0
	s_barrier
	s_add_i32 s22, s41, s13
	v_lshl_add_u64 v[226:227], v[226:227], 0, s[92:93]
	s_mov_b32 m0, s22
	ds_read_b128 v[194:197], v175 offset:49152
	ds_read_b128 v[198:201], v175 offset:50176
	ds_read_b128 v[202:205], v175 offset:51200
	ds_read_b128 v[206:209], v175 offset:52224
	ds_read_b128 v[210:213], v175 offset:53248
	ds_read_b128 v[214:217], v175 offset:54272
	ds_read_b128 v[218:221], v175 offset:55296
	ds_read_b128 v[222:225], v175 offset:56320
	global_load_lds_dwordx4 v[226:227], off
	s_add_i32 m0, s22, 0x2000
	s_add_u32 s20, s20, 0x40080
	v_lshl_add_u64 v[226:227], v[228:229], 0, s[92:93]
	s_addc_u32 s21, s21, 0
	s_add_i32 s22, s42, s13
	global_load_lds_dwordx4 v[226:227], off
	v_lshl_add_u64 v[226:227], s[20:21], 0, v[0:1]
	s_mov_b32 m0, s22
	s_nop 0
	global_load_lds_dwordx4 v[226:227], off
	v_lshl_add_u64 v[226:227], s[20:21], 0, v[14:15]
	s_add_i32 m0, s22, 0x2000
	s_nop 0
	global_load_lds_dwordx4 v[226:227], off
	v_lshl_add_u64 v[226:227], v[230:231], 0, s[92:93]
	s_mov_b32 m0, s30
	s_nop 0
	global_load_lds_dwordx4 v[226:227], off
	v_lshl_add_u64 v[226:227], v[232:233], 0, s[92:93]
	s_mov_b32 m0, s31
	s_nop 0
	global_load_lds_dwordx4 v[226:227], off
	s_waitcnt vmcnt(8)
	s_waitcnt lgkmcnt(0)
	s_barrier
	s_setprio 1
	s_waitcnt lgkmcnt(0)
	v_mfma_f32_16x16x32_bf16 v[66:69], v[134:137], v[194:197], v[66:69]
	v_mfma_f32_16x16x32_bf16 v[66:69], v[148:151], v[198:201], v[66:69]
	v_mfma_f32_16x16x32_bf16 v[58:61], v[152:155], v[194:197], v[58:61]
	v_mfma_f32_16x16x32_bf16 v[58:61], v[156:159], v[198:201], v[58:61]
	v_mfma_f32_16x16x32_bf16 v[50:53], v[134:137], v[202:205], v[50:53]
	v_mfma_f32_16x16x32_bf16 v[50:53], v[148:151], v[206:209], v[50:53]
	v_mfma_f32_16x16x32_bf16 v[42:45], v[152:155], v[202:205], v[42:45]
	v_mfma_f32_16x16x32_bf16 v[42:45], v[156:159], v[206:209], v[42:45]
	v_mfma_f32_16x16x32_bf16 v[34:37], v[134:137], v[210:213], v[34:37]
	v_mfma_f32_16x16x32_bf16 v[34:37], v[148:151], v[214:217], v[34:37]
	v_mfma_f32_16x16x32_bf16 v[26:29], v[152:155], v[210:213], v[26:29]
	v_mfma_f32_16x16x32_bf16 v[26:29], v[156:159], v[214:217], v[26:29]
	v_mfma_f32_16x16x32_bf16 v[18:21], v[134:137], v[218:221], v[18:21]
	v_mfma_f32_16x16x32_bf16 v[18:21], v[148:151], v[222:225], v[18:21]
	v_mfma_f32_16x16x32_bf16 v[6:9], v[152:155], v[218:221], v[6:9]
	v_mfma_f32_16x16x32_bf16 v[6:9], v[156:159], v[222:225], v[6:9]
	s_setprio 0
	s_setprio 1
	v_mfma_f32_16x16x32_bf16 v[62:65], v[160:163], v[194:197], v[62:65]
	v_mfma_f32_16x16x32_bf16 v[62:65], v[182:185], v[198:201], v[62:65]
	v_mfma_f32_16x16x32_bf16 v[54:57], v[186:189], v[194:197], v[54:57]
	v_mfma_f32_16x16x32_bf16 v[54:57], v[190:193], v[198:201], v[54:57]
	v_mfma_f32_16x16x32_bf16 v[46:49], v[160:163], v[202:205], v[46:49]
	v_mfma_f32_16x16x32_bf16 v[46:49], v[182:185], v[206:209], v[46:49]
	v_mfma_f32_16x16x32_bf16 v[38:41], v[186:189], v[202:205], v[38:41]
	v_mfma_f32_16x16x32_bf16 v[38:41], v[190:193], v[206:209], v[38:41]
	v_mfma_f32_16x16x32_bf16 v[30:33], v[160:163], v[210:213], v[30:33]
	v_mfma_f32_16x16x32_bf16 v[30:33], v[182:185], v[214:217], v[30:33]
	v_mfma_f32_16x16x32_bf16 v[22:25], v[186:189], v[210:213], v[22:25]
	v_mfma_f32_16x16x32_bf16 v[22:25], v[190:193], v[214:217], v[22:25]
	v_mfma_f32_16x16x32_bf16 v[10:13], v[160:163], v[218:221], v[10:13]
	v_mfma_f32_16x16x32_bf16 v[10:13], v[182:185], v[222:225], v[10:13]
	v_mfma_f32_16x16x32_bf16 v[2:5], v[186:189], v[218:221], v[2:5]
	v_mfma_f32_16x16x32_bf16 v[2:5], v[190:193], v[222:225], v[2:5]
	s_setprio 0
	s_barrier
	s_add_i32 s40, s40, 2
	s_add_u32 s4, s4, 0x100
	s_addc_u32 s5, s5, 0
	s_add_u32 s38, s38, 0x100
	s_addc_u32 s39, s39, 0
	s_cmp_gt_u32 s40, 13
	s_cbranch_scc0 .LBB0_893
	s_and_b64 vcc, exec, s[8:9]
	s_cbranch_vccz .LBB0_896
	s_barrier

.Lg3_relax_w1:
	s_waitcnt vmcnt(16)
	s_branch .Lg3_join_w1
